# v29 + rw_scan step schedule: the six LDS reads of step t+2 issued together after the state update instead of inside the DPP reduction gaps (gaps filled with s_nop 0)
# speedup vs baseline: 1.0025x; 1.0015x over previous
.LBB0_774:
	s_and_b32 s11, s10, 1
	s_mul_i32 s0, s11, 0x5400
	s_add_i32 s0, s0, 16
	v_lshl_add_u32 v126, v87, 2, s0
	v_add3_u32 v124, s0, v91, v92
	ds_read_b32 v204, v124 offset:1280
	ds_read_b128 v[184:187], v126 offset:0
	ds_read_b128 v[196:199], v126 offset:768
	ds_read_b128 v[188:191], v126 offset:256
	ds_read_b128 v[200:203], v126 offset:1024
	ds_read_b128 v[192:195], v126 offset:512
	ds_read_b32 v226, v124 offset:2624
	ds_read_b128 v[206:209], v126 offset:1344
	ds_read_b128 v[218:221], v126 offset:2112
	ds_read_b128 v[210:213], v126 offset:1600
	ds_read_b128 v[222:225], v126 offset:2368
	ds_read_b128 v[214:217], v126 offset:1856
	s_waitcnt lgkmcnt(6)
	v_pk_mul_f32 v[250:251], v[8:9], v[184:185]
	v_pk_mul_f32 v[252:253], v[204:205], v[196:197] op_sel_hi:[0,1]
	v_pk_fma_f32 v[250:251], v[10:11], v[186:187], v[250:251]
	v_pk_mul_f32 v[254:255], v[204:205], v[198:199] op_sel_hi:[0,1]
	v_add_f32_e32 v14, v250, v251
	v_pk_fma_f32 v[252:253], v[8:9], v[188:189], v[252:253]
	v_pk_fma_f32 v[254:255], v[10:11], v[190:191], v[254:255]
	v_add_f32_dpp v14, v14, v14 quad_perm:[1,0,3,2] row_mask:0xf bank_mask:0xf bound_ctrl:1
	ds_read_b32 v248, v124 offset:3968
	ds_read_b128 v[228:231], v126 offset:2688
	v_add_f32_dpp v14, v14, v14 quad_perm:[2,3,0,1] row_mask:0xf bank_mask:0xf bound_ctrl:1
	ds_read_b128 v[240:243], v126 offset:3456
	ds_read_b128 v[232:235], v126 offset:2944
	v_add_f32_dpp v14, v14, v14 row_half_mirror row_mask:0xf bank_mask:0xf bound_ctrl:1
	ds_read_b128 v[244:247], v126 offset:3712
	ds_read_b128 v[236:239], v126 offset:3200
	v_add_f32_dpp v14, v14, v14 row_mirror row_mask:0xf bank_mask:0xf bound_ctrl:1
	v_pk_fma_f32 v[8:9], v[14:15], v[192:193], v[252:253] op_sel_hi:[0,1,1]
	v_pk_fma_f32 v[10:11], v[14:15], v[194:195], v[254:255] op_sel_hi:[0,1,1]
	s_waitcnt lgkmcnt(6)
	v_pk_mul_f32 v[250:251], v[8:9], v[206:207]
	v_pk_mul_f32 v[252:253], v[226:227], v[218:219] op_sel_hi:[0,1]
	v_pk_fma_f32 v[250:251], v[10:11], v[208:209], v[250:251]
	v_pk_mul_f32 v[254:255], v[226:227], v[220:221] op_sel_hi:[0,1]
	v_add_f32_e32 v14, v250, v251
	v_pk_fma_f32 v[252:253], v[8:9], v[210:211], v[252:253]
	v_pk_fma_f32 v[254:255], v[10:11], v[212:213], v[254:255]
	v_add_f32_dpp v14, v14, v14 quad_perm:[1,0,3,2] row_mask:0xf bank_mask:0xf bound_ctrl:1
	v_pk_mul_f32 v[12:13], v[8:9], v[200:201]
	s_nop 0
	v_add_f32_dpp v14, v14, v14 quad_perm:[2,3,0,1] row_mask:0xf bank_mask:0xf bound_ctrl:1
	v_pk_fma_f32 v[12:13], v[10:11], v[202:203], v[12:13]
	s_nop 0
	v_add_f32_dpp v14, v14, v14 row_half_mirror row_mask:0xf bank_mask:0xf bound_ctrl:1
	v_add_f32_e32 v18, v12, v13
	s_nop 0
	v_add_f32_dpp v14, v14, v14 row_mirror row_mask:0xf bank_mask:0xf bound_ctrl:1
	v_pk_fma_f32 v[8:9], v[14:15], v[214:215], v[252:253] op_sel_hi:[0,1,1]
	v_pk_fma_f32 v[10:11], v[14:15], v[216:217], v[254:255] op_sel_hi:[0,1,1]
	ds_read_b32 v204, v124 offset:5312
	ds_read_b128 v[184:187], v126 offset:4032
	ds_read_b128 v[196:199], v126 offset:4800
	ds_read_b128 v[188:191], v126 offset:4288
	ds_read_b128 v[200:203], v126 offset:5056
	ds_read_b128 v[192:195], v126 offset:4544
	s_waitcnt lgkmcnt(6)
	v_pk_mul_f32 v[250:251], v[8:9], v[228:229]
	v_pk_mul_f32 v[252:253], v[248:249], v[240:241] op_sel_hi:[0,1]
	v_pk_fma_f32 v[250:251], v[10:11], v[230:231], v[250:251]
	v_pk_mul_f32 v[254:255], v[248:249], v[242:243] op_sel_hi:[0,1]
	v_add_f32_e32 v14, v250, v251
	v_pk_fma_f32 v[252:253], v[8:9], v[232:233], v[252:253]
	v_pk_fma_f32 v[254:255], v[10:11], v[234:235], v[254:255]
	v_add_f32_dpp v14, v14, v14 quad_perm:[1,0,3,2] row_mask:0xf bank_mask:0xf bound_ctrl:1
	v_pk_mul_f32 v[12:13], v[8:9], v[222:223]
	s_nop 0
	v_add_f32_dpp v14, v14, v14 quad_perm:[2,3,0,1] row_mask:0xf bank_mask:0xf bound_ctrl:1
	v_pk_fma_f32 v[12:13], v[10:11], v[224:225], v[12:13]
	s_nop 0
	v_add_f32_dpp v14, v14, v14 row_half_mirror row_mask:0xf bank_mask:0xf bound_ctrl:1
	v_add_f32_e32 v19, v12, v13
	s_nop 0
	v_add_f32_dpp v14, v14, v14 row_mirror row_mask:0xf bank_mask:0xf bound_ctrl:1
	v_pk_fma_f32 v[8:9], v[14:15], v[236:237], v[252:253] op_sel_hi:[0,1,1]
	v_pk_fma_f32 v[10:11], v[14:15], v[238:239], v[254:255] op_sel_hi:[0,1,1]
	ds_read_b32 v226, v124 offset:6656
	ds_read_b128 v[206:209], v126 offset:5376
	ds_read_b128 v[218:221], v126 offset:6144
	ds_read_b128 v[210:213], v126 offset:5632
	ds_read_b128 v[222:225], v126 offset:6400
	ds_read_b128 v[214:217], v126 offset:5888
	s_waitcnt lgkmcnt(6)
	v_pk_mul_f32 v[250:251], v[8:9], v[184:185]
	v_pk_mul_f32 v[252:253], v[204:205], v[196:197] op_sel_hi:[0,1]
	v_pk_fma_f32 v[250:251], v[10:11], v[186:187], v[250:251]
	v_pk_mul_f32 v[254:255], v[204:205], v[198:199] op_sel_hi:[0,1]
	v_add_f32_e32 v14, v250, v251
	v_pk_fma_f32 v[252:253], v[8:9], v[188:189], v[252:253]
	v_pk_fma_f32 v[254:255], v[10:11], v[190:191], v[254:255]
	v_add_f32_dpp v14, v14, v14 quad_perm:[1,0,3,2] row_mask:0xf bank_mask:0xf bound_ctrl:1
	v_pk_mul_f32 v[12:13], v[8:9], v[244:245]
	s_nop 0
	v_add_f32_dpp v14, v14, v14 quad_perm:[2,3,0,1] row_mask:0xf bank_mask:0xf bound_ctrl:1
	v_pk_fma_f32 v[12:13], v[10:11], v[246:247], v[12:13]
	s_nop 0
	v_add_f32_dpp v14, v14, v14 row_half_mirror row_mask:0xf bank_mask:0xf bound_ctrl:1
	v_add_f32_e32 v20, v12, v13
	s_nop 0
	v_add_f32_dpp v14, v14, v14 row_mirror row_mask:0xf bank_mask:0xf bound_ctrl:1
	v_pk_fma_f32 v[8:9], v[14:15], v[192:193], v[252:253] op_sel_hi:[0,1,1]
	v_pk_fma_f32 v[10:11], v[14:15], v[194:195], v[254:255] op_sel_hi:[0,1,1]
	ds_read_b32 v248, v124 offset:8000
	ds_read_b128 v[228:231], v126 offset:6720
	ds_read_b128 v[240:243], v126 offset:7488
	ds_read_b128 v[232:235], v126 offset:6976
	ds_read_b128 v[244:247], v126 offset:7744
	ds_read_b128 v[236:239], v126 offset:7232
	s_waitcnt lgkmcnt(6)
	v_pk_mul_f32 v[250:251], v[8:9], v[206:207]
	v_pk_mul_f32 v[252:253], v[226:227], v[218:219] op_sel_hi:[0,1]
	v_pk_fma_f32 v[250:251], v[10:11], v[208:209], v[250:251]
	v_pk_mul_f32 v[254:255], v[226:227], v[220:221] op_sel_hi:[0,1]
	v_add_f32_e32 v14, v250, v251
	v_pk_fma_f32 v[252:253], v[8:9], v[210:211], v[252:253]
	v_pk_fma_f32 v[254:255], v[10:11], v[212:213], v[254:255]
	v_add_f32_dpp v14, v14, v14 quad_perm:[1,0,3,2] row_mask:0xf bank_mask:0xf bound_ctrl:1
	v_pk_mul_f32 v[12:13], v[8:9], v[200:201]
	s_nop 0
	v_add_f32_dpp v14, v14, v14 quad_perm:[2,3,0,1] row_mask:0xf bank_mask:0xf bound_ctrl:1
	v_pk_fma_f32 v[12:13], v[10:11], v[202:203], v[12:13]
	s_nop 0
	v_add_f32_dpp v14, v14, v14 row_half_mirror row_mask:0xf bank_mask:0xf bound_ctrl:1
	v_add_f32_e32 v21, v12, v13
	s_nop 0
	v_add_f32_dpp v14, v14, v14 row_mirror row_mask:0xf bank_mask:0xf bound_ctrl:1
	v_pk_fma_f32 v[8:9], v[14:15], v[214:215], v[252:253] op_sel_hi:[0,1,1]
	v_pk_fma_f32 v[10:11], v[14:15], v[216:217], v[254:255] op_sel_hi:[0,1,1]
	ds_read_b32 v204, v124 offset:9344
	ds_read_b128 v[184:187], v126 offset:8064
	ds_read_b128 v[196:199], v126 offset:8832
	ds_read_b128 v[188:191], v126 offset:8320
	ds_read_b128 v[200:203], v126 offset:9088
	ds_read_b128 v[192:195], v126 offset:8576
	s_waitcnt lgkmcnt(6)
	v_pk_mul_f32 v[250:251], v[8:9], v[228:229]
	v_pk_mul_f32 v[252:253], v[248:249], v[240:241] op_sel_hi:[0,1]
	v_pk_fma_f32 v[250:251], v[10:11], v[230:231], v[250:251]
	v_pk_mul_f32 v[254:255], v[248:249], v[242:243] op_sel_hi:[0,1]
	v_add_f32_e32 v14, v250, v251
	v_pk_fma_f32 v[252:253], v[8:9], v[232:233], v[252:253]
	v_pk_fma_f32 v[254:255], v[10:11], v[234:235], v[254:255]
	v_add_f32_dpp v14, v14, v14 quad_perm:[1,0,3,2] row_mask:0xf bank_mask:0xf bound_ctrl:1
	v_pk_mul_f32 v[12:13], v[8:9], v[222:223]
	s_nop 0
	v_add_f32_dpp v14, v14, v14 quad_perm:[2,3,0,1] row_mask:0xf bank_mask:0xf bound_ctrl:1
	v_pk_fma_f32 v[12:13], v[10:11], v[224:225], v[12:13]
	s_nop 0
	v_add_f32_dpp v14, v14, v14 row_half_mirror row_mask:0xf bank_mask:0xf bound_ctrl:1
	v_add_f32_e32 v22, v12, v13
	s_nop 0
	v_add_f32_dpp v14, v14, v14 row_mirror row_mask:0xf bank_mask:0xf bound_ctrl:1
	v_pk_fma_f32 v[8:9], v[14:15], v[236:237], v[252:253] op_sel_hi:[0,1,1]
	v_pk_fma_f32 v[10:11], v[14:15], v[238:239], v[254:255] op_sel_hi:[0,1,1]
	ds_read_b32 v226, v124 offset:10688
	ds_read_b128 v[206:209], v126 offset:9408
	ds_read_b128 v[218:221], v126 offset:10176
	ds_read_b128 v[210:213], v126 offset:9664
	ds_read_b128 v[222:225], v126 offset:10432
	ds_read_b128 v[214:217], v126 offset:9920
	s_waitcnt lgkmcnt(6)
	v_pk_mul_f32 v[250:251], v[8:9], v[184:185]
	v_pk_mul_f32 v[252:253], v[204:205], v[196:197] op_sel_hi:[0,1]
	v_pk_fma_f32 v[250:251], v[10:11], v[186:187], v[250:251]
	v_pk_mul_f32 v[254:255], v[204:205], v[198:199] op_sel_hi:[0,1]
	v_add_f32_e32 v14, v250, v251
	v_pk_fma_f32 v[252:253], v[8:9], v[188:189], v[252:253]
	v_pk_fma_f32 v[254:255], v[10:11], v[190:191], v[254:255]
	v_add_f32_dpp v14, v14, v14 quad_perm:[1,0,3,2] row_mask:0xf bank_mask:0xf bound_ctrl:1
	v_pk_mul_f32 v[12:13], v[8:9], v[244:245]
	s_nop 0
	v_add_f32_dpp v14, v14, v14 quad_perm:[2,3,0,1] row_mask:0xf bank_mask:0xf bound_ctrl:1
	v_pk_fma_f32 v[12:13], v[10:11], v[246:247], v[12:13]
	s_nop 0
	v_add_f32_dpp v14, v14, v14 row_half_mirror row_mask:0xf bank_mask:0xf bound_ctrl:1
	v_add_f32_e32 v23, v12, v13
	s_nop 0
	v_add_f32_dpp v14, v14, v14 row_mirror row_mask:0xf bank_mask:0xf bound_ctrl:1
	v_pk_fma_f32 v[8:9], v[14:15], v[192:193], v[252:253] op_sel_hi:[0,1,1]
	v_pk_fma_f32 v[10:11], v[14:15], v[194:195], v[254:255] op_sel_hi:[0,1,1]
	ds_read_b32 v248, v124 offset:12032
	ds_read_b128 v[228:231], v126 offset:10752
	ds_read_b128 v[240:243], v126 offset:11520
	ds_read_b128 v[232:235], v126 offset:11008
	ds_read_b128 v[244:247], v126 offset:11776
	ds_read_b128 v[236:239], v126 offset:11264
	s_waitcnt lgkmcnt(6)
	v_pk_mul_f32 v[250:251], v[8:9], v[206:207]
	v_pk_mul_f32 v[252:253], v[226:227], v[218:219] op_sel_hi:[0,1]
	v_pk_fma_f32 v[250:251], v[10:11], v[208:209], v[250:251]
	v_pk_mul_f32 v[254:255], v[226:227], v[220:221] op_sel_hi:[0,1]
	v_add_f32_e32 v14, v250, v251
	v_pk_fma_f32 v[252:253], v[8:9], v[210:211], v[252:253]
	v_pk_fma_f32 v[254:255], v[10:11], v[212:213], v[254:255]
	v_add_f32_dpp v14, v14, v14 quad_perm:[1,0,3,2] row_mask:0xf bank_mask:0xf bound_ctrl:1
	v_pk_mul_f32 v[12:13], v[8:9], v[200:201]
	s_nop 0
	v_add_f32_dpp v14, v14, v14 quad_perm:[2,3,0,1] row_mask:0xf bank_mask:0xf bound_ctrl:1
	v_pk_fma_f32 v[12:13], v[10:11], v[202:203], v[12:13]
	s_nop 0
	v_add_f32_dpp v14, v14, v14 row_half_mirror row_mask:0xf bank_mask:0xf bound_ctrl:1
	v_add_f32_e32 v24, v12, v13
	s_nop 0
	v_add_f32_dpp v14, v14, v14 row_mirror row_mask:0xf bank_mask:0xf bound_ctrl:1
	v_pk_fma_f32 v[8:9], v[14:15], v[214:215], v[252:253] op_sel_hi:[0,1,1]
	v_pk_fma_f32 v[10:11], v[14:15], v[216:217], v[254:255] op_sel_hi:[0,1,1]
	ds_read_b32 v204, v124 offset:13376
	ds_read_b128 v[184:187], v126 offset:12096
	ds_read_b128 v[196:199], v126 offset:12864
	ds_read_b128 v[188:191], v126 offset:12352
	ds_read_b128 v[200:203], v126 offset:13120
	ds_read_b128 v[192:195], v126 offset:12608
	s_waitcnt lgkmcnt(6)
	v_pk_mul_f32 v[250:251], v[8:9], v[228:229]
	v_pk_mul_f32 v[252:253], v[248:249], v[240:241] op_sel_hi:[0,1]
	v_pk_fma_f32 v[250:251], v[10:11], v[230:231], v[250:251]
	v_pk_mul_f32 v[254:255], v[248:249], v[242:243] op_sel_hi:[0,1]
	v_add_f32_e32 v14, v250, v251
	v_pk_fma_f32 v[252:253], v[8:9], v[232:233], v[252:253]
	v_pk_fma_f32 v[254:255], v[10:11], v[234:235], v[254:255]
	v_add_f32_dpp v14, v14, v14 quad_perm:[1,0,3,2] row_mask:0xf bank_mask:0xf bound_ctrl:1
	v_pk_mul_f32 v[12:13], v[8:9], v[222:223]
	s_nop 0
	v_add_f32_dpp v14, v14, v14 quad_perm:[2,3,0,1] row_mask:0xf bank_mask:0xf bound_ctrl:1
	v_pk_fma_f32 v[12:13], v[10:11], v[224:225], v[12:13]
	s_nop 0
	v_add_f32_dpp v14, v14, v14 row_half_mirror row_mask:0xf bank_mask:0xf bound_ctrl:1
	v_add_f32_e32 v25, v12, v13
	s_nop 0
	v_add_f32_dpp v14, v14, v14 row_mirror row_mask:0xf bank_mask:0xf bound_ctrl:1
	v_pk_fma_f32 v[8:9], v[14:15], v[236:237], v[252:253] op_sel_hi:[0,1,1]
	v_pk_fma_f32 v[10:11], v[14:15], v[238:239], v[254:255] op_sel_hi:[0,1,1]
	ds_read_b32 v226, v124 offset:14720
	ds_read_b128 v[206:209], v126 offset:13440
	ds_read_b128 v[218:221], v126 offset:14208
	ds_read_b128 v[210:213], v126 offset:13696
	ds_read_b128 v[222:225], v126 offset:14464
	ds_read_b128 v[214:217], v126 offset:13952
	s_waitcnt vmcnt(0)
	s_xor_b32 s0, s11, 1
	s_mulk_i32 s0, 0x5400
	v_add_u32_e32 v82, s0, v79
	v_lshlrev_b32_e32 v34, 16, v74
	v_and_b32_e32 v35, 0xffff0000, v74
	v_lshlrev_b32_e32 v36, 16, v75
	v_and_b32_e32 v37, 0xffff0000, v75
	v_lshl_add_u32 v83, v50, 2, v82
	v_pk_mul_f32 v[38:39], v[0:1], v[34:35]
	v_pk_mul_f32 v[40:41], v[2:3], v[36:37]
	v_lshlrev_b32_e32 v120, 16, v72
	v_pk_mul_f32 v[42:43], v[78:79], v[38:39] op_sel_hi:[0,1] neg_lo:[1,0] neg_hi:[1,0]
	v_pk_mul_f32 v[44:45], v[78:79], v[40:41] op_sel_hi:[0,1] neg_lo:[1,0] neg_hi:[1,0]
	v_and_b32_e32 v121, 0xffff0000, v72
	v_lshlrev_b32_e32 v122, 16, v73
	v_and_b32_e32 v123, 0xffff0000, v73
	ds_write_b128 v83, v[42:45]
	v_lshlrev_b32_e32 v38, 16, v76
	v_and_b32_e32 v39, 0xffff0000, v76
	v_lshlrev_b32_e32 v40, 16, v77
	v_and_b32_e32 v41, 0xffff0000, v77
	v_pk_add_f32 v[38:39], v[38:39], 1.0 op_sel_hi:[1,0] neg_lo:[1,0] neg_hi:[1,0]
	v_pk_add_f32 v[40:41], v[40:41], 1.0 op_sel_hi:[1,0] neg_lo:[1,0] neg_hi:[1,0]
	v_lshl_add_u32 v85, v48, 2, v82
	ds_write_b128 v83, v[38:41] offset:256
	v_pk_mul_f32 v[38:39], v[42:43], v[120:121] neg_lo:[1,0] neg_hi:[1,0]
	v_pk_mul_f32 v[40:41], v[44:45], v[122:123] neg_lo:[1,0] neg_hi:[1,0]
	v_pk_add_f32 v[120:121], v[120:121], -1.0 op_sel_hi:[1,0]
	v_pk_add_f32 v[122:123], v[122:123], -1.0 op_sel_hi:[1,0]
	ds_write_b128 v83, v[38:41] offset:512
	v_pk_fma_f32 v[120:121], v[4:5], v[120:121], 1.0 op_sel_hi:[1,1,0]
	v_pk_fma_f32 v[122:123], v[6:7], v[122:123], 1.0 op_sel_hi:[1,1,0]
	v_lshlrev_b32_e32 v42, 16, v62
	v_and_b32_e32 v43, 0xffff0000, v62
	v_pk_mul_f32 v[120:121], v[120:121], v[34:35]
	v_pk_mul_f32 v[122:123], v[122:123], v[36:37]
	v_lshlrev_b32_e32 v44, 16, v63
	v_and_b32_e32 v45, 0xffff0000, v63
	v_lshlrev_b32_e32 v84, 16, v102
	ds_write_b128 v83, v[120:123] offset:768
	ds_write_b128 v83, v[42:45] offset:1024
	ds_write_b32 v85, v84 offset:1280
	s_cmpk_eq_i32 s6, 0x20e0
	s_cbranch_scc1 .Lscan_pf_skip
	v_add_u32_e32 v131, v132, v131
	s_cmp_eq_u32 s10, 14
	s_cbranch_scc0 .Lscan_pf_nox
	v_mov_b32_e32 v131, v133

.Lscan_pf_skip:
	s_waitcnt lgkmcnt(12)
	v_pk_mul_f32 v[250:251], v[8:9], v[184:185]
	v_pk_mul_f32 v[252:253], v[204:205], v[196:197] op_sel_hi:[0,1]
	v_pk_fma_f32 v[250:251], v[10:11], v[186:187], v[250:251]
	v_pk_mul_f32 v[254:255], v[204:205], v[198:199] op_sel_hi:[0,1]
	v_add_f32_e32 v14, v250, v251
	v_pk_fma_f32 v[252:253], v[8:9], v[188:189], v[252:253]
	v_pk_fma_f32 v[254:255], v[10:11], v[190:191], v[254:255]
	v_add_f32_dpp v14, v14, v14 quad_perm:[1,0,3,2] row_mask:0xf bank_mask:0xf bound_ctrl:1
	v_pk_mul_f32 v[12:13], v[8:9], v[244:245]
	s_nop 0
	v_add_f32_dpp v14, v14, v14 quad_perm:[2,3,0,1] row_mask:0xf bank_mask:0xf bound_ctrl:1
	v_pk_fma_f32 v[12:13], v[10:11], v[246:247], v[12:13]
	s_nop 0
	v_add_f32_dpp v14, v14, v14 row_half_mirror row_mask:0xf bank_mask:0xf bound_ctrl:1
	v_add_f32_e32 v26, v12, v13
	s_nop 0
	v_add_f32_dpp v14, v14, v14 row_mirror row_mask:0xf bank_mask:0xf bound_ctrl:1
	v_pk_fma_f32 v[8:9], v[14:15], v[192:193], v[252:253] op_sel_hi:[0,1,1]
	v_pk_fma_f32 v[10:11], v[14:15], v[194:195], v[254:255] op_sel_hi:[0,1,1]
	ds_read_b32 v248, v124 offset:16064
	ds_read_b128 v[228:231], v126 offset:14784
	ds_read_b128 v[240:243], v126 offset:15552
	ds_read_b128 v[232:235], v126 offset:15040
	ds_read_b128 v[244:247], v126 offset:15808
	ds_read_b128 v[236:239], v126 offset:15296
	s_waitcnt lgkmcnt(12)
	v_pk_mul_f32 v[250:251], v[8:9], v[206:207]
	v_pk_mul_f32 v[252:253], v[226:227], v[218:219] op_sel_hi:[0,1]
	v_pk_fma_f32 v[250:251], v[10:11], v[208:209], v[250:251]
	v_pk_mul_f32 v[254:255], v[226:227], v[220:221] op_sel_hi:[0,1]
	v_add_f32_e32 v14, v250, v251
	v_pk_fma_f32 v[252:253], v[8:9], v[210:211], v[252:253]
	v_pk_fma_f32 v[254:255], v[10:11], v[212:213], v[254:255]
	v_add_f32_dpp v14, v14, v14 quad_perm:[1,0,3,2] row_mask:0xf bank_mask:0xf bound_ctrl:1
	v_pk_mul_f32 v[12:13], v[8:9], v[200:201]
	s_nop 0
	v_add_f32_dpp v14, v14, v14 quad_perm:[2,3,0,1] row_mask:0xf bank_mask:0xf bound_ctrl:1
	v_pk_fma_f32 v[12:13], v[10:11], v[202:203], v[12:13]
	s_nop 0
	v_add_f32_dpp v14, v14, v14 row_half_mirror row_mask:0xf bank_mask:0xf bound_ctrl:1
	v_add_f32_e32 v27, v12, v13
	s_nop 0
	v_add_f32_dpp v14, v14, v14 row_mirror row_mask:0xf bank_mask:0xf bound_ctrl:1
	v_pk_fma_f32 v[8:9], v[14:15], v[214:215], v[252:253] op_sel_hi:[0,1,1]
	v_pk_fma_f32 v[10:11], v[14:15], v[216:217], v[254:255] op_sel_hi:[0,1,1]
	ds_read_b32 v204, v124 offset:17408
	ds_read_b128 v[184:187], v126 offset:16128
	ds_read_b128 v[196:199], v126 offset:16896
	ds_read_b128 v[188:191], v126 offset:16384
	ds_read_b128 v[200:203], v126 offset:17152
	ds_read_b128 v[192:195], v126 offset:16640
	s_waitcnt lgkmcnt(6)
	v_pk_mul_f32 v[250:251], v[8:9], v[228:229]
	v_pk_mul_f32 v[252:253], v[248:249], v[240:241] op_sel_hi:[0,1]
	v_pk_fma_f32 v[250:251], v[10:11], v[230:231], v[250:251]
	v_pk_mul_f32 v[254:255], v[248:249], v[242:243] op_sel_hi:[0,1]
	v_add_f32_e32 v14, v250, v251
	v_pk_fma_f32 v[252:253], v[8:9], v[232:233], v[252:253]
	v_pk_fma_f32 v[254:255], v[10:11], v[234:235], v[254:255]
	v_add_f32_dpp v14, v14, v14 quad_perm:[1,0,3,2] row_mask:0xf bank_mask:0xf bound_ctrl:1
	v_pk_mul_f32 v[12:13], v[8:9], v[222:223]
	s_nop 0
	v_add_f32_dpp v14, v14, v14 quad_perm:[2,3,0,1] row_mask:0xf bank_mask:0xf bound_ctrl:1
	v_pk_fma_f32 v[12:13], v[10:11], v[224:225], v[12:13]
	s_nop 0
	v_add_f32_dpp v14, v14, v14 row_half_mirror row_mask:0xf bank_mask:0xf bound_ctrl:1
	v_add_f32_e32 v28, v12, v13
	s_nop 0
	v_add_f32_dpp v14, v14, v14 row_mirror row_mask:0xf bank_mask:0xf bound_ctrl:1
	v_pk_fma_f32 v[8:9], v[14:15], v[236:237], v[252:253] op_sel_hi:[0,1,1]
	v_pk_fma_f32 v[10:11], v[14:15], v[238:239], v[254:255] op_sel_hi:[0,1,1]
	ds_read_b32 v226, v124 offset:18752
	ds_read_b128 v[206:209], v126 offset:17472
	ds_read_b128 v[218:221], v126 offset:18240
	ds_read_b128 v[210:213], v126 offset:17728
	ds_read_b128 v[222:225], v126 offset:18496
	ds_read_b128 v[214:217], v126 offset:17984
	s_waitcnt lgkmcnt(6)
	v_pk_mul_f32 v[250:251], v[8:9], v[184:185]
	v_pk_mul_f32 v[252:253], v[204:205], v[196:197] op_sel_hi:[0,1]
	v_pk_fma_f32 v[250:251], v[10:11], v[186:187], v[250:251]
	v_pk_mul_f32 v[254:255], v[204:205], v[198:199] op_sel_hi:[0,1]
	v_add_f32_e32 v14, v250, v251
	v_pk_fma_f32 v[252:253], v[8:9], v[188:189], v[252:253]
	v_pk_fma_f32 v[254:255], v[10:11], v[190:191], v[254:255]
	v_add_f32_dpp v14, v14, v14 quad_perm:[1,0,3,2] row_mask:0xf bank_mask:0xf bound_ctrl:1
	v_pk_mul_f32 v[12:13], v[8:9], v[244:245]
	s_nop 0
	v_add_f32_dpp v14, v14, v14 quad_perm:[2,3,0,1] row_mask:0xf bank_mask:0xf bound_ctrl:1
	v_pk_fma_f32 v[12:13], v[10:11], v[246:247], v[12:13]
	s_nop 0
	v_add_f32_dpp v14, v14, v14 row_half_mirror row_mask:0xf bank_mask:0xf bound_ctrl:1
	v_add_f32_e32 v29, v12, v13
	s_nop 0
	v_add_f32_dpp v14, v14, v14 row_mirror row_mask:0xf bank_mask:0xf bound_ctrl:1
	v_pk_fma_f32 v[8:9], v[14:15], v[192:193], v[252:253] op_sel_hi:[0,1,1]
	v_pk_fma_f32 v[10:11], v[14:15], v[194:195], v[254:255] op_sel_hi:[0,1,1]
	ds_read_b32 v248, v124 offset:20096
	ds_read_b128 v[228:231], v126 offset:18816
	ds_read_b128 v[240:243], v126 offset:19584
	ds_read_b128 v[232:235], v126 offset:19072
	ds_read_b128 v[244:247], v126 offset:19840
	ds_read_b128 v[236:239], v126 offset:19328
	s_waitcnt lgkmcnt(6)
	v_pk_mul_f32 v[250:251], v[8:9], v[206:207]
	v_pk_mul_f32 v[252:253], v[226:227], v[218:219] op_sel_hi:[0,1]
	v_pk_fma_f32 v[250:251], v[10:11], v[208:209], v[250:251]
	v_pk_mul_f32 v[254:255], v[226:227], v[220:221] op_sel_hi:[0,1]
	v_add_f32_e32 v14, v250, v251
	v_pk_fma_f32 v[252:253], v[8:9], v[210:211], v[252:253]
	v_pk_fma_f32 v[254:255], v[10:11], v[212:213], v[254:255]
	v_add_f32_dpp v14, v14, v14 quad_perm:[1,0,3,2] row_mask:0xf bank_mask:0xf bound_ctrl:1
	v_pk_mul_f32 v[12:13], v[8:9], v[200:201]
	s_nop 0
	v_add_f32_dpp v14, v14, v14 quad_perm:[2,3,0,1] row_mask:0xf bank_mask:0xf bound_ctrl:1
	v_pk_fma_f32 v[12:13], v[10:11], v[202:203], v[12:13]
	s_nop 0
	v_add_f32_dpp v14, v14, v14 row_half_mirror row_mask:0xf bank_mask:0xf bound_ctrl:1
	v_add_f32_e32 v30, v12, v13
	s_nop 0
	v_add_f32_dpp v14, v14, v14 row_mirror row_mask:0xf bank_mask:0xf bound_ctrl:1
	v_pk_fma_f32 v[8:9], v[14:15], v[214:215], v[252:253] op_sel_hi:[0,1,1]
	v_pk_fma_f32 v[10:11], v[14:15], v[216:217], v[254:255] op_sel_hi:[0,1,1]
	ds_read_b32 v204, v124 offset:21440
	ds_read_b128 v[184:187], v126 offset:20160
	ds_read_b128 v[196:199], v126 offset:20928
	ds_read_b128 v[188:191], v126 offset:20416
	ds_read_b128 v[200:203], v126 offset:21184
	ds_read_b128 v[192:195], v126 offset:20672
	s_waitcnt lgkmcnt(6)
	v_pk_mul_f32 v[250:251], v[8:9], v[228:229]
	v_pk_mul_f32 v[252:253], v[248:249], v[240:241] op_sel_hi:[0,1]
	v_pk_fma_f32 v[250:251], v[10:11], v[230:231], v[250:251]
	v_pk_mul_f32 v[254:255], v[248:249], v[242:243] op_sel_hi:[0,1]
	v_add_f32_e32 v14, v250, v251
	v_pk_fma_f32 v[252:253], v[8:9], v[232:233], v[252:253]
	v_pk_fma_f32 v[254:255], v[10:11], v[234:235], v[254:255]
	v_add_f32_dpp v14, v14, v14 quad_perm:[1,0,3,2] row_mask:0xf bank_mask:0xf bound_ctrl:1
	v_pk_mul_f32 v[12:13], v[8:9], v[222:223]
	s_nop 0
	v_add_f32_dpp v14, v14, v14 quad_perm:[2,3,0,1] row_mask:0xf bank_mask:0xf bound_ctrl:1
	v_pk_fma_f32 v[12:13], v[10:11], v[224:225], v[12:13]
	s_nop 0
	v_add_f32_dpp v14, v14, v14 row_half_mirror row_mask:0xf bank_mask:0xf bound_ctrl:1
	v_add_f32_e32 v31, v12, v13
	s_nop 0
	v_add_f32_dpp v14, v14, v14 row_mirror row_mask:0xf bank_mask:0xf bound_ctrl:1
	v_pk_fma_f32 v[8:9], v[14:15], v[236:237], v[252:253] op_sel_hi:[0,1,1]
	v_pk_fma_f32 v[10:11], v[14:15], v[238:239], v[254:255] op_sel_hi:[0,1,1]
	s_waitcnt lgkmcnt(0)
	v_pk_mul_f32 v[250:251], v[8:9], v[184:185]
	v_pk_mul_f32 v[252:253], v[204:205], v[196:197] op_sel_hi:[0,1]
	v_pk_fma_f32 v[250:251], v[10:11], v[186:187], v[250:251]
	v_pk_mul_f32 v[254:255], v[204:205], v[198:199] op_sel_hi:[0,1]
	v_add_f32_e32 v14, v250, v251
	v_pk_fma_f32 v[252:253], v[8:9], v[188:189], v[252:253]
	v_pk_fma_f32 v[254:255], v[10:11], v[190:191], v[254:255]
	v_add_f32_dpp v14, v14, v14 quad_perm:[1,0,3,2] row_mask:0xf bank_mask:0xf bound_ctrl:1
	v_pk_mul_f32 v[12:13], v[8:9], v[244:245]
	s_nop 0
	v_add_f32_dpp v14, v14, v14 quad_perm:[2,3,0,1] row_mask:0xf bank_mask:0xf bound_ctrl:1
	v_pk_fma_f32 v[12:13], v[10:11], v[246:247], v[12:13]
	s_nop 0
	v_add_f32_dpp v14, v14, v14 row_half_mirror row_mask:0xf bank_mask:0xf bound_ctrl:1
	v_add_f32_e32 v32, v12, v13
	s_nop 0
	v_add_f32_dpp v14, v14, v14 row_mirror row_mask:0xf bank_mask:0xf bound_ctrl:1
	v_pk_fma_f32 v[8:9], v[14:15], v[192:193], v[252:253] op_sel_hi:[0,1,1]
	v_pk_fma_f32 v[10:11], v[14:15], v[194:195], v[254:255] op_sel_hi:[0,1,1]
	v_pk_mul_f32 v[12:13], v[8:9], v[200:201]
	v_add_f32_dpp v34, v18, v18 row_mirror row_mask:0xf bank_mask:0x3 bound_ctrl:1
	v_pk_fma_f32 v[12:13], v[10:11], v[202:203], v[12:13]
	v_add_f32_dpp v35, v19, v19 row_mirror row_mask:0xf bank_mask:0x3 bound_ctrl:1
	v_add_f32_dpp v36, v20, v20 row_mirror row_mask:0xf bank_mask:0x3 bound_ctrl:1
	v_add_f32_e32 v33, v12, v13
	v_add_f32_dpp v37, v21, v21 row_mirror row_mask:0xf bank_mask:0x3 bound_ctrl:1
	v_add_f32_dpp v38, v22, v22 row_mirror row_mask:0xf bank_mask:0x3 bound_ctrl:1
	v_add_f32_dpp v39, v23, v23 row_mirror row_mask:0xf bank_mask:0x3 bound_ctrl:1
	v_add_f32_dpp v40, v24, v24 row_mirror row_mask:0xf bank_mask:0x3 bound_ctrl:1
	v_add_f32_dpp v41, v25, v25 row_mirror row_mask:0xf bank_mask:0x3 bound_ctrl:1
	v_add_f32_dpp v34, v26, v26 row_mirror row_mask:0xf bank_mask:0xc bound_ctrl:1
	v_add_f32_dpp v35, v27, v27 row_mirror row_mask:0xf bank_mask:0xc bound_ctrl:1
	v_add_f32_dpp v36, v28, v28 row_mirror row_mask:0xf bank_mask:0xc bound_ctrl:1
	v_add_f32_dpp v37, v29, v29 row_mirror row_mask:0xf bank_mask:0xc bound_ctrl:1
	v_add_f32_dpp v38, v30, v30 row_mirror row_mask:0xf bank_mask:0xc bound_ctrl:1
	v_add_f32_dpp v39, v31, v31 row_mirror row_mask:0xf bank_mask:0xc bound_ctrl:1
	v_add_f32_dpp v40, v32, v32 row_mirror row_mask:0xf bank_mask:0xc bound_ctrl:1
	v_add_f32_dpp v41, v33, v33 row_mirror row_mask:0xf bank_mask:0xc bound_ctrl:1
	v_add_f32_dpp v42, v34, v34 row_half_mirror row_mask:0xf bank_mask:0x5 bound_ctrl:1
	v_add_f32_dpp v43, v35, v35 row_half_mirror row_mask:0xf bank_mask:0x5 bound_ctrl:1
	v_add_f32_dpp v44, v36, v36 row_half_mirror row_mask:0xf bank_mask:0x5 bound_ctrl:1
	v_add_f32_dpp v45, v37, v37 row_half_mirror row_mask:0xf bank_mask:0x5 bound_ctrl:1
	v_add_f32_dpp v42, v38, v38 row_half_mirror row_mask:0xf bank_mask:0xa bound_ctrl:1
	v_add_f32_dpp v43, v39, v39 row_half_mirror row_mask:0xf bank_mask:0xa bound_ctrl:1
	v_add_f32_dpp v44, v40, v40 row_half_mirror row_mask:0xf bank_mask:0xa bound_ctrl:1
	v_add_f32_dpp v45, v41, v41 row_half_mirror row_mask:0xf bank_mask:0xa bound_ctrl:1
	v_cndmask_b32_e64 v80, v44, v42, s[42:43]
	v_cndmask_b32_e64 v121, v42, v44, s[42:43]
	v_cndmask_b32_e64 v82, v45, v43, s[42:43]
	v_cndmask_b32_e64 v122, v43, v45, s[42:43]
	s_nop 0
	s_nop 0
	v_add_f32_dpp v13, v121, v80 quad_perm:[2,3,0,1] row_mask:0xf bank_mask:0xf bound_ctrl:1
	v_add_f32_dpp v14, v122, v82 quad_perm:[2,3,0,1] row_mask:0xf bank_mask:0xf bound_ctrl:1
	v_cndmask_b32_e64 v12, v13, v14, s[44:45]
	v_cndmask_b32_e64 v13, v14, v13, s[44:45]
	v_lshl_add_u32 v16, v100, 11, v99
	v_add_u32_e32 v100, v132, v100
	v_add_f32_dpp v13, v12, v13 quad_perm:[1,0,3,2] row_mask:0xf bank_mask:0xf bound_ctrl:1
	s_cmp_eq_u32 s10, 15
	s_cbranch_scc0 .Lscan_tail_nox
	v_mov_b32_e32 v100, v101
